# P2 rope-key GEMM epilogue: 8 rs1 loads batched (was serialized load+vmcnt(0) behind stores); pass C norm_w loads batched
# speedup vs baseline: 1.0058x; 1.0058x over previous
.LBB0_245:
	v_lshl_add_u32 v142, s4, 8, v148
	v_ashrrev_i32_e32 v143, 31, v142
	v_lshl_add_u64 v[144:145], v[142:143], 2, s[92:93]
	global_load_dword v229, v[144:145], off
	global_load_dword v230, v[144:145], off offset:64
	global_load_dword v231, v[144:145], off offset:128
	global_load_dword v232, v[144:145], off offset:192
	global_load_dword v233, v[144:145], off offset:512
	global_load_dword v234, v[144:145], off offset:576
	global_load_dword v235, v[144:145], off offset:640
	global_load_dword v236, v[144:145], off offset:704
	v_lshl_or_b32 v140, s31, 8, v150
	v_cmp_gt_i32_e64 s[2:3], 64, v140
	s_waitcnt vmcnt(0)
	v_mov_b32_e32 v146, v229
	v_mov_b32_e32 v147, v146
	s_and_saveexec_b64 s[4:5], s[2:3]
	s_cbranch_execz .LBB0_247
	v_mov_b32_e32 v156, v146
	v_mov_b32_e32 v157, v146
	v_pk_mul_f32 v[124:125], v[124:125], v[146:147]
	v_pk_mul_f32 v[126:127], v[126:127], v[156:157]
	v_pk_mul_f32 v[156:157], v[122:123], v[156:157]
	v_pk_mul_f32 v[122:123], v[120:121], v[146:147]
	v_cvt_pk_bf16_f32 v120, v124, v125
	v_mov_b64_e32 v[124:125], s[56:57]
	v_mad_i64_i32 v[124:125], s[8:9], v142, s29, v[124:125]
	v_ashrrev_i32_e32 v141, 31, v140
	v_cvt_pk_bf16_f32 v121, v126, v127
	v_cvt_pk_bf16_f32 v122, v122, v123
	v_cvt_pk_bf16_f32 v123, v156, v157
	v_lshl_add_u64 v[124:125], v[140:141], 1, v[124:125]
	global_store_dwordx4 v[124:125], v[120:123], off

.LBB0_249:
	s_nop 1
	v_or_b32_e32 v112, 16, v142
	v_ashrrev_i32_e32 v113, 31, v112
	v_lshl_add_u64 v[114:115], v[112:113], 2, s[92:93]
	s_nop 1
	v_mov_b32_e32 v114, v230
	v_mov_b32_e32 v115, v114
	s_and_saveexec_b64 s[4:5], s[2:3]
	s_cbranch_execz .LBB0_251
	v_mov_b32_e32 v116, v114
	v_mov_b32_e32 v117, v114
	v_pk_mul_f32 v[108:109], v[108:109], v[114:115]
	v_pk_mul_f32 v[110:111], v[110:111], v[116:117]
	v_pk_mul_f32 v[116:117], v[106:107], v[116:117]
	v_pk_mul_f32 v[106:107], v[104:105], v[114:115]
	v_cvt_pk_bf16_f32 v104, v108, v109
	v_mov_b64_e32 v[108:109], s[56:57]
	v_mad_i64_i32 v[108:109], s[10:11], v112, s29, v[108:109]
	v_ashrrev_i32_e32 v141, 31, v140
	v_cvt_pk_bf16_f32 v105, v110, v111
	v_cvt_pk_bf16_f32 v106, v106, v107
	v_cvt_pk_bf16_f32 v107, v116, v117
	v_lshl_add_u64 v[108:109], v[140:141], 1, v[108:109]
	global_store_dwordx4 v[108:109], v[104:107], off

.LBB0_253:
	s_nop 1
	v_or_b32_e32 v96, 32, v142
	v_ashrrev_i32_e32 v97, 31, v96
	v_lshl_add_u64 v[98:99], v[96:97], 2, s[92:93]
	s_nop 1
	v_mov_b32_e32 v98, v231
	v_mov_b32_e32 v99, v98
	s_and_saveexec_b64 s[8:9], s[2:3]
	s_cbranch_execz .LBB0_255
	v_mov_b32_e32 v100, v98
	v_mov_b32_e32 v101, v98
	v_pk_mul_f32 v[92:93], v[92:93], v[98:99]
	v_pk_mul_f32 v[94:95], v[94:95], v[100:101]
	v_pk_mul_f32 v[100:101], v[90:91], v[100:101]
	v_pk_mul_f32 v[90:91], v[88:89], v[98:99]
	v_cvt_pk_bf16_f32 v88, v92, v93
	v_mov_b64_e32 v[92:93], s[56:57]
	v_mad_i64_i32 v[92:93], s[10:11], v96, s29, v[92:93]
	v_ashrrev_i32_e32 v141, 31, v140
	v_cvt_pk_bf16_f32 v89, v94, v95
	v_cvt_pk_bf16_f32 v90, v90, v91
	v_cvt_pk_bf16_f32 v91, v100, v101
	v_lshl_add_u64 v[92:93], v[140:141], 1, v[92:93]
	global_store_dwordx4 v[92:93], v[88:91], off

.LBB0_257:
	s_nop 1
	v_or_b32_e32 v80, 48, v142
	v_ashrrev_i32_e32 v81, 31, v80
	v_lshl_add_u64 v[82:83], v[80:81], 2, s[92:93]
	s_nop 1
	v_mov_b32_e32 v82, v232
	v_mov_b32_e32 v83, v82
	s_and_saveexec_b64 s[8:9], s[2:3]
	s_cbranch_execz .LBB0_259
	v_mov_b32_e32 v84, v82
	v_mov_b32_e32 v85, v82
	v_pk_mul_f32 v[76:77], v[76:77], v[82:83]
	v_pk_mul_f32 v[78:79], v[78:79], v[84:85]
	v_pk_mul_f32 v[84:85], v[74:75], v[84:85]
	v_pk_mul_f32 v[74:75], v[72:73], v[82:83]
	v_cvt_pk_bf16_f32 v72, v76, v77
	v_mov_b64_e32 v[76:77], s[56:57]
	v_mad_i64_i32 v[76:77], s[10:11], v80, s29, v[76:77]
	v_ashrrev_i32_e32 v141, 31, v140
	v_cvt_pk_bf16_f32 v73, v78, v79
	v_cvt_pk_bf16_f32 v74, v74, v75
	v_cvt_pk_bf16_f32 v75, v84, v85
	v_lshl_add_u64 v[76:77], v[140:141], 1, v[76:77]
	global_store_dwordx4 v[76:77], v[72:75], off

.LBB0_261:
	s_nop 1
	v_mov_b32_e32 v64, v233
	s_nop 0
	v_add_u32_e32 v66, 0x80, v142
	v_mov_b32_e32 v65, v64
	s_and_saveexec_b64 s[8:9], s[2:3]
	s_cbranch_execz .LBB0_263
	v_mov_b32_e32 v68, v64
	v_mov_b32_e32 v69, v64
	v_pk_mul_f32 v[60:61], v[60:61], v[64:65]
	v_pk_mul_f32 v[62:63], v[62:63], v[68:69]
	v_pk_mul_f32 v[68:69], v[58:59], v[68:69]
	v_pk_mul_f32 v[58:59], v[56:57], v[64:65]
	v_cvt_pk_bf16_f32 v56, v60, v61
	v_mov_b64_e32 v[60:61], s[56:57]
	v_mad_i64_i32 v[60:61], s[10:11], v66, s29, v[60:61]
	v_ashrrev_i32_e32 v141, 31, v140
	v_cvt_pk_bf16_f32 v57, v62, v63
	v_cvt_pk_bf16_f32 v58, v58, v59
	v_cvt_pk_bf16_f32 v59, v68, v69
	v_lshl_add_u64 v[60:61], v[140:141], 1, v[60:61]
	global_store_dwordx4 v[60:61], v[56:59], off

.LBB0_265:
	s_nop 1
	v_mov_b32_e32 v48, v234
	s_nop 0
	v_add_u32_e32 v50, 0x90, v142
	v_mov_b32_e32 v49, v48
	s_and_saveexec_b64 s[8:9], s[2:3]
	s_cbranch_execz .LBB0_267
	v_mov_b32_e32 v52, v48
	v_mov_b32_e32 v53, v48
	v_pk_mul_f32 v[44:45], v[44:45], v[48:49]
	v_pk_mul_f32 v[46:47], v[46:47], v[52:53]
	v_pk_mul_f32 v[52:53], v[42:43], v[52:53]
	v_pk_mul_f32 v[42:43], v[40:41], v[48:49]
	v_cvt_pk_bf16_f32 v40, v44, v45
	v_mov_b64_e32 v[44:45], s[56:57]
	v_mad_i64_i32 v[44:45], s[10:11], v50, s29, v[44:45]
	v_ashrrev_i32_e32 v141, 31, v140
	v_cvt_pk_bf16_f32 v41, v46, v47
	v_cvt_pk_bf16_f32 v42, v42, v43
	v_cvt_pk_bf16_f32 v43, v52, v53
	v_lshl_add_u64 v[44:45], v[140:141], 1, v[44:45]
	global_store_dwordx4 v[44:45], v[40:43], off

.LBB0_269:
	s_nop 1
	v_mov_b32_e32 v32, v235
	s_nop 0
	v_add_u32_e32 v34, 0xa0, v142
	v_mov_b32_e32 v33, v32
	s_and_saveexec_b64 s[8:9], s[2:3]
	s_cbranch_execz .LBB0_271
	v_mov_b32_e32 v36, v32
	v_mov_b32_e32 v37, v32
	v_pk_mul_f32 v[28:29], v[28:29], v[32:33]
	v_pk_mul_f32 v[30:31], v[30:31], v[36:37]
	v_pk_mul_f32 v[36:37], v[26:27], v[36:37]
	v_pk_mul_f32 v[26:27], v[24:25], v[32:33]
	v_cvt_pk_bf16_f32 v24, v28, v29
	v_mov_b64_e32 v[28:29], s[56:57]
	v_mad_i64_i32 v[28:29], s[10:11], v34, s29, v[28:29]
	v_ashrrev_i32_e32 v141, 31, v140
	v_cvt_pk_bf16_f32 v25, v30, v31
	v_cvt_pk_bf16_f32 v26, v26, v27
	v_cvt_pk_bf16_f32 v27, v36, v37
	v_lshl_add_u64 v[28:29], v[140:141], 1, v[28:29]
	global_store_dwordx4 v[28:29], v[24:27], off

.LBB0_273:
	s_nop 1
	v_mov_b32_e32 v16, v236
	s_nop 0
	v_add_u32_e32 v18, 0xb0, v142
	v_mov_b32_e32 v17, v16
	s_and_saveexec_b64 s[8:9], s[2:3]
	s_cbranch_execz .LBB0_276
	v_mov_b32_e32 v20, v16
	v_mov_b32_e32 v21, v16
	v_pk_mul_f32 v[12:13], v[12:13], v[16:17]
	v_pk_mul_f32 v[14:15], v[14:15], v[20:21]
	v_pk_mul_f32 v[20:21], v[10:11], v[20:21]
	v_pk_mul_f32 v[10:11], v[8:9], v[16:17]
	v_cvt_pk_bf16_f32 v8, v12, v13
	v_mov_b64_e32 v[12:13], s[56:57]
	v_mad_i64_i32 v[12:13], s[2:3], v18, s29, v[12:13]
	v_ashrrev_i32_e32 v141, 31, v140
	v_cvt_pk_bf16_f32 v9, v14, v15
	v_cvt_pk_bf16_f32 v10, v10, v11
	v_cvt_pk_bf16_f32 v11, v20, v21
	v_lshl_add_u64 v[12:13], v[140:141], 1, v[12:13]
	global_store_dwordx4 v[12:13], v[8:11], off
	s_or_b64 exec, exec, s[8:9]
	s_and_b64 vcc, exec, s[4:5]
	s_cbranch_vccnz .LBB0_277
